# removed the redundant setprio 0 then 1 pair between the two MFMA blocks of each GEMM phase
# speedup vs baseline: 1.0007x; 1.0007x over previous
; #define PG8_STAGE(bufoff, gbase, voff) do { _Pragma("unroll") for (int _i = 0; _i < 2; ++_i) \
;         __builtin_amdgcn_global_load_lds((const unsigned*)((const char*)(gbase) + (voff)[_i]), (LAS unsigned*)(lds + (bufoff) + ldsw + _i * 8192), 16, 0, 0); } while (0)
; #define PG8_LDA(dst, b, h) do { _Pragma("unroll") for (int m = 0; m < 4; ++m) _Pragma("unroll") for (int k = 0; k < 2; ++k) dst[m][k] = *(const LAS bf16x8*)(lds + PG8_SA(b, h) + aoff + m * 2048 + k * 1024); } while (0)
; #define PG8_LDB(dst, b, h) do { _Pragma("unroll") for (int n = 0; n < 2; ++n) _Pragma("unroll") for (int k = 0; k < 2; ++k) dst[n][k] = *(const LAS bf16x8*)(lds + PG8_SB(b, h) + boff + n * 2048 + k * 1024); } while (0)
; #define PG8_MMA(ai, bj, At, Bt) do { __builtin_amdgcn_s_setprio(1); _Pragma("unroll") for (int m = 0; m < 4; ++m) _Pragma("unroll") for (int n = 0; n < 2; ++n) _Pragma("unroll") for (int k = 0; k < 2; ++k) \
;         acc[ai][bj][m][n] = __builtin_amdgcn_mfma_f32_16x16x32_bf16(Bt[n][k], At[m][k], acc[ai][bj][m][n], 0, 0, 0); __builtin_amdgcn_s_setprio(0); } while (0)
; #define PG8_WAIT_V(n) asm volatile("s_waitcnt vmcnt(" #n ")" ::: "memory")
; #define PG8_WAIT_L(n) asm volatile("s_waitcnt lgkmcnt(" #n ")" ::: "memory")
; #define PG8_BAR __builtin_amdgcn_s_barrier()
; #define PG8_SCHED __builtin_amdgcn_sched_barrier(0)
; template <class Epi>
; __device__ __forceinline__ void gemm_phase(LAS unsigned char* lds, const Gemm g, const StaticOrder& S, const Epi& E, const int tid) {
;     ...
;             const char* a2 = last ? nA : cA + (size_t)(t + 2) * kstep; const char* b2 = last ? nB : cB + (size_t)(t + 2) * kstep;
;             const char* a3 = a2 + kstep; const char* b3 = b2 + kstep;
;             PG8_LDB(B0, 0, 0); PG8_LDB(B1, 0, 1); PG8_SCHED; PG8_LDA(At, 0, 0); PG8_STAGE(PG8_SA(1, 1), a1 + hstepA, voffA);
;             PG8_WAIT_V(8); PG8_WAIT_L(0); PG8_BAR; PG8_MMA(0, 0, At, B0); PG8_MMA(0, 1, At, B1); PG8_BAR; PG8_SCHED;
;             PG8_LDA(At, 0, 1); PG8_STAGE(PG8_SB(0, 0), b2, voffB); PG8_STAGE(PG8_SB(0, 1), b2 + hstepB, voffB); PG8_STAGE(PG8_SA(0, 0), a2, voffA);
;             PG8_WAIT_V(8); PG8_WAIT_L(0); PG8_BAR; PG8_MMA(1, 0, At, B0); PG8_MMA(1, 1, At, B1); PG8_BAR; PG8_SCHED;
.LBB0_35:
	s_add_u32 s28, s6, 0xfff80080
	s_addc_u32 s29, s7, -1
	s_add_i32 s54, 0, 0x10000
	s_cmp_eq_u32 s53, 12
	s_cselect_b32 s31, s15, s29
	s_cselect_b32 s30, s21, s28
	s_cselect_b32 s29, s19, s52
	s_cselect_b32 s28, s50, s51
	s_add_i32 s68, 0, 0x14000
	v_add_u32_e32 v100, s54, v189
	v_add_u32_e32 v158, s68, v189
	ds_read_b128 v[64:67], v100
	ds_read_b128 v[76:79], v100 offset:1024
	ds_read_b128 v[88:91], v100 offset:2048
	ds_read_b128 v[100:103], v100 offset:3072
	ds_read_b128 v[146:149], v158
	ds_read_b128 v[150:153], v158 offset:1024
	ds_read_b128 v[154:157], v158 offset:2048
	ds_read_b128 v[158:161], v158 offset:3072
	v_lshl_add_u64 v[176:177], s[6:7], 0, v[168:169]
	s_add_i32 m0, s40, 0xc000
	ds_read_b128 v[172:175], v193
	ds_read_b128 v[194:197], v193 offset:1024
	ds_read_b128 v[198:201], v193 offset:2048
	ds_read_b128 v[216:219], v193 offset:3072
	ds_read_b128 v[220:223], v193 offset:4096
	ds_read_b128 v[224:227], v193 offset:5120
	ds_read_b128 v[228:231], v193 offset:6144
	ds_read_b128 v[232:235], v193 offset:7168
	global_load_lds_dwordx4 v[176:177], off
	v_lshl_add_u64 v[176:177], s[6:7], 0, v[170:171]
	s_add_i32 m0, s40, 0xe000
	s_nop 0
	global_load_lds_dwordx4 v[176:177], off
	s_waitcnt vmcnt(8)
	s_waitcnt lgkmcnt(0)
	s_barrier
	s_setprio 1
	s_waitcnt lgkmcnt(0)
	v_mfma_f32_16x16x32_bf16 v[142:145], v[64:67], v[172:175], v[142:145]
	v_mfma_f32_16x16x32_bf16 v[138:141], v[88:91], v[172:175], v[138:141]
	v_mfma_f32_16x16x32_bf16 v[124:127], v[64:67], v[198:201], v[124:127]
	v_mfma_f32_16x16x32_bf16 v[120:123], v[88:91], v[198:201], v[120:123]
	v_mfma_f32_16x16x32_bf16 v[108:111], v[64:67], v[220:223], v[108:111]
	v_mfma_f32_16x16x32_bf16 v[104:107], v[88:91], v[220:223], v[104:107]
	v_mfma_f32_16x16x32_bf16 v[84:87], v[64:67], v[228:231], v[84:87]
	v_mfma_f32_16x16x32_bf16 v[80:83], v[88:91], v[228:231], v[80:83]
	v_mfma_f32_16x16x32_bf16 v[142:145], v[76:79], v[194:197], v[142:145]
	v_mfma_f32_16x16x32_bf16 v[138:141], v[100:103], v[194:197], v[138:141]
	v_mfma_f32_16x16x32_bf16 v[124:127], v[76:79], v[216:219], v[124:127]
	v_mfma_f32_16x16x32_bf16 v[120:123], v[100:103], v[216:219], v[120:123]
	v_mfma_f32_16x16x32_bf16 v[108:111], v[76:79], v[224:227], v[108:111]
	v_mfma_f32_16x16x32_bf16 v[104:107], v[100:103], v[224:227], v[104:107]
	v_mfma_f32_16x16x32_bf16 v[84:87], v[76:79], v[232:235], v[84:87]
	v_mfma_f32_16x16x32_bf16 v[80:83], v[100:103], v[232:235], v[80:83]
	v_mfma_f32_16x16x32_bf16 v[132:135], v[146:149], v[172:175], v[132:135]
	v_mfma_f32_16x16x32_bf16 v[128:131], v[154:157], v[172:175], v[128:131]
	v_mfma_f32_16x16x32_bf16 v[116:119], v[146:149], v[198:201], v[116:119]
	v_mfma_f32_16x16x32_bf16 v[112:115], v[154:157], v[198:201], v[112:115]
	v_mfma_f32_16x16x32_bf16 v[96:99], v[146:149], v[220:223], v[96:99]
	v_mfma_f32_16x16x32_bf16 v[92:95], v[154:157], v[220:223], v[92:95]
	v_mfma_f32_16x16x32_bf16 v[72:75], v[146:149], v[228:231], v[72:75]
	v_mfma_f32_16x16x32_bf16 v[68:71], v[154:157], v[228:231], v[68:71]
	v_mfma_f32_16x16x32_bf16 v[132:135], v[150:153], v[194:197], v[132:135]
	v_mfma_f32_16x16x32_bf16 v[128:131], v[158:161], v[194:197], v[128:131]
	v_mfma_f32_16x16x32_bf16 v[116:119], v[150:153], v[216:219], v[116:119]
	v_mfma_f32_16x16x32_bf16 v[112:115], v[158:161], v[216:219], v[112:115]
	v_mfma_f32_16x16x32_bf16 v[96:99], v[150:153], v[224:227], v[96:99]
	v_mfma_f32_16x16x32_bf16 v[92:95], v[158:161], v[224:227], v[92:95]
	v_mfma_f32_16x16x32_bf16 v[72:75], v[150:153], v[232:235], v[72:75]
	v_mfma_f32_16x16x32_bf16 v[68:71], v[158:161], v[232:235], v[68:71]
	s_setprio 0
	s_barrier
	s_add_i32 s54, s54, s39
	v_lshl_add_u64 v[176:177], s[28:29], 0, v[136:137]
	s_mov_b32 m0, s54
	ds_read_b128 v[172:175], v193 offset:16384
	ds_read_b128 v[194:197], v193 offset:17408
	ds_read_b128 v[198:201], v193 offset:18432
	ds_read_b128 v[216:219], v193 offset:19456
	ds_read_b128 v[220:223], v193 offset:20480
	ds_read_b128 v[224:227], v193 offset:21504
	ds_read_b128 v[228:231], v193 offset:22528
	ds_read_b128 v[232:235], v193 offset:23552
	global_load_lds_dwordx4 v[176:177], off
	s_add_i32 m0, s54, 0x2000
	s_add_u32 s54, s28, 0x80000
	v_lshl_add_u64 v[190:191], s[28:29], 0, v[162:163]
	s_addc_u32 s55, s29, 0
	s_add_i32 s68, s68, s39
	global_load_lds_dwordx4 v[190:191], off
	v_lshl_add_u64 v[202:203], s[54:55], 0, v[136:137]
	s_mov_b32 m0, s68
	v_lshl_add_u64 v[236:237], s[30:31], 0, v[164:165]
	global_load_lds_dwordx4 v[202:203], off
	v_lshl_add_u64 v[202:203], s[54:55], 0, v[162:163]
	s_add_i32 m0, s68, 0x2000
	s_nop 0
	global_load_lds_dwordx4 v[202:203], off
	v_lshl_add_u64 v[202:203], s[30:31], 0, v[166:167]
	s_mov_b32 m0, s40
	s_nop 0
	global_load_lds_dwordx4 v[202:203], off
	s_mov_b32 m0, s41
	s_nop 0
	global_load_lds_dwordx4 v[236:237], off
	s_waitcnt vmcnt(8)
	s_waitcnt lgkmcnt(0)
	s_barrier
; #define PG8_STAGE(bufoff, gbase, voff) do { _Pragma("unroll") for (int _i = 0; _i < 2; ++_i) \
;         __builtin_amdgcn_global_load_lds((const unsigned*)((const char*)(gbase) + (voff)[_i]), (LAS unsigned*)(lds + (bufoff) + ldsw + _i * 8192), 16, 0, 0); } while (0)
; #define PG8_LDA(dst, b, h) do { _Pragma("unroll") for (int m = 0; m < 4; ++m) _Pragma("unroll") for (int k = 0; k < 2; ++k) dst[m][k] = *(const LAS bf16x8*)(lds + PG8_SA(b, h) + aoff + m * 2048 + k * 1024); } while (0)
; #define PG8_LDB(dst, b, h) do { _Pragma("unroll") for (int n = 0; n < 2; ++n) _Pragma("unroll") for (int k = 0; k < 2; ++k) dst[n][k] = *(const LAS bf16x8*)(lds + PG8_SB(b, h) + boff + n * 2048 + k * 1024); } while (0)
; #define PG8_MMA(ai, bj, At, Bt) do { __builtin_amdgcn_s_setprio(1); _Pragma("unroll") for (int m = 0; m < 4; ++m) _Pragma("unroll") for (int n = 0; n < 2; ++n) _Pragma("unroll") for (int k = 0; k < 2; ++k) \
;         acc[ai][bj][m][n] = __builtin_amdgcn_mfma_f32_16x16x32_bf16(Bt[n][k], At[m][k], acc[ai][bj][m][n], 0, 0, 0); __builtin_amdgcn_s_setprio(0); } while (0)
; #define PG8_WAIT_V(n) asm volatile("s_waitcnt vmcnt(" #n ")" ::: "memory")
; #define PG8_WAIT_L(n) asm volatile("s_waitcnt lgkmcnt(" #n ")" ::: "memory")
; #define PG8_BAR __builtin_amdgcn_s_barrier()
; #define PG8_SCHED __builtin_amdgcn_sched_barrier(0)
; template <class Epi>
; __device__ __forceinline__ void gemm_phase(LAS unsigned char* lds, const Gemm g, const StaticOrder& S, const Epi& E, const int tid) {
;     ...
;             PG8_WAIT_V(8); PG8_WAIT_L(0); PG8_BAR; PG8_MMA(1, 0, At, B0); PG8_MMA(1, 1, At, B1); PG8_BAR; PG8_SCHED;
;             PG8_LDB(B0, 1, 0); PG8_LDB(B1, 1, 1); PG8_SCHED; PG8_LDA(At, 1, 0); PG8_STAGE(PG8_SA(0, 1), a2 + hstepA, voffA);
;             PG8_WAIT_V(8); PG8_WAIT_L(0); PG8_BAR; PG8_MMA(0, 0, At, B0); PG8_MMA(0, 1, At, B1); PG8_BAR; PG8_SCHED;
	s_setprio 1
	s_waitcnt lgkmcnt(0)
	v_mfma_f32_16x16x32_bf16 v[60:63], v[64:67], v[172:175], v[60:63]
	v_mfma_f32_16x16x32_bf16 v[56:59], v[88:91], v[172:175], v[56:59]
	v_mfma_f32_16x16x32_bf16 v[44:47], v[64:67], v[198:201], v[44:47]
	v_mfma_f32_16x16x32_bf16 v[40:43], v[88:91], v[198:201], v[40:43]
	v_mfma_f32_16x16x32_bf16 v[28:31], v[64:67], v[220:223], v[28:31]
	v_mfma_f32_16x16x32_bf16 v[24:27], v[88:91], v[220:223], v[24:27]
	v_mfma_f32_16x16x32_bf16 v[12:15], v[64:67], v[228:231], v[12:15]
	v_mfma_f32_16x16x32_bf16 v[8:11], v[88:91], v[228:231], v[8:11]
	v_mfma_f32_16x16x32_bf16 v[60:63], v[76:79], v[194:197], v[60:63]
	v_mfma_f32_16x16x32_bf16 v[56:59], v[100:103], v[194:197], v[56:59]
	v_mfma_f32_16x16x32_bf16 v[44:47], v[76:79], v[216:219], v[44:47]
	v_mfma_f32_16x16x32_bf16 v[40:43], v[100:103], v[216:219], v[40:43]
	v_mfma_f32_16x16x32_bf16 v[28:31], v[76:79], v[224:227], v[28:31]
	v_mfma_f32_16x16x32_bf16 v[24:27], v[100:103], v[224:227], v[24:27]
	v_mfma_f32_16x16x32_bf16 v[12:15], v[76:79], v[232:235], v[12:15]
	v_mfma_f32_16x16x32_bf16 v[8:11], v[100:103], v[232:235], v[8:11]
	v_mfma_f32_16x16x32_bf16 v[52:55], v[146:149], v[172:175], v[52:55]
	v_mfma_f32_16x16x32_bf16 v[48:51], v[154:157], v[172:175], v[48:51]
	v_mfma_f32_16x16x32_bf16 v[36:39], v[146:149], v[198:201], v[36:39]
	v_mfma_f32_16x16x32_bf16 v[32:35], v[154:157], v[198:201], v[32:35]
	v_mfma_f32_16x16x32_bf16 v[20:23], v[146:149], v[220:223], v[20:23]
	v_mfma_f32_16x16x32_bf16 v[16:19], v[154:157], v[220:223], v[16:19]
	v_mfma_f32_16x16x32_bf16 v[4:7], v[146:149], v[228:231], v[4:7]
	v_mfma_f32_16x16x32_bf16 v[0:3], v[154:157], v[228:231], v[0:3]
	v_mfma_f32_16x16x32_bf16 v[52:55], v[150:153], v[194:197], v[52:55]
	v_mfma_f32_16x16x32_bf16 v[48:51], v[158:161], v[194:197], v[48:51]
	v_mfma_f32_16x16x32_bf16 v[36:39], v[150:153], v[216:219], v[36:39]
	v_mfma_f32_16x16x32_bf16 v[32:35], v[158:161], v[216:219], v[32:35]
	v_mfma_f32_16x16x32_bf16 v[20:23], v[150:153], v[224:227], v[20:23]
	v_mfma_f32_16x16x32_bf16 v[16:19], v[158:161], v[224:227], v[16:19]
	v_mfma_f32_16x16x32_bf16 v[4:7], v[150:153], v[232:235], v[4:7]
	v_mfma_f32_16x16x32_bf16 v[0:3], v[158:161], v[232:235], v[0:3]
	s_setprio 0
	s_barrier
	s_add_i32 s54, 0, 0x18000
	s_add_i32 s55, 0, 0x1c000
	v_add_u32_e32 v100, s54, v189
	v_add_u32_e32 v158, s55, v189
	ds_read_b128 v[64:67], v100
	ds_read_b128 v[76:79], v100 offset:1024
	ds_read_b128 v[88:91], v100 offset:2048
	ds_read_b128 v[100:103], v100 offset:3072
	ds_read_b128 v[146:149], v158
	ds_read_b128 v[150:153], v158 offset:1024
	ds_read_b128 v[154:157], v158 offset:2048
	ds_read_b128 v[158:161], v158 offset:3072
	s_add_u32 s30, s30, 0x80000
	s_addc_u32 s31, s31, 0
	s_mov_b32 m0, s42
	v_lshl_add_u64 v[238:239], s[30:31], 0, v[166:167]
	ds_read_b128 v[172:175], v193 offset:32768
	ds_read_b128 v[194:197], v193 offset:33792
	ds_read_b128 v[198:201], v193 offset:34816
	ds_read_b128 v[216:219], v193 offset:35840
	ds_read_b128 v[220:223], v193 offset:36864
	ds_read_b128 v[224:227], v193 offset:37888
	ds_read_b128 v[228:231], v193 offset:38912
	ds_read_b128 v[232:235], v193 offset:39936
	global_load_lds_dwordx4 v[238:239], off
	v_lshl_add_u64 v[238:239], s[30:31], 0, v[164:165]
	s_mov_b32 m0, s43
	s_nop 0
	global_load_lds_dwordx4 v[238:239], off
	s_waitcnt vmcnt(8)
	s_waitcnt lgkmcnt(0)
	s_barrier
	s_setprio 1
	s_waitcnt lgkmcnt(0)
	v_mfma_f32_16x16x32_bf16 v[142:145], v[64:67], v[172:175], v[142:145]
	v_mfma_f32_16x16x32_bf16 v[138:141], v[88:91], v[172:175], v[138:141]
	v_mfma_f32_16x16x32_bf16 v[124:127], v[64:67], v[198:201], v[124:127]
	v_mfma_f32_16x16x32_bf16 v[120:123], v[88:91], v[198:201], v[120:123]
	v_mfma_f32_16x16x32_bf16 v[108:111], v[64:67], v[220:223], v[108:111]
	v_mfma_f32_16x16x32_bf16 v[104:107], v[88:91], v[220:223], v[104:107]
	v_mfma_f32_16x16x32_bf16 v[84:87], v[64:67], v[228:231], v[84:87]
	v_mfma_f32_16x16x32_bf16 v[80:83], v[88:91], v[228:231], v[80:83]
	v_mfma_f32_16x16x32_bf16 v[142:145], v[76:79], v[194:197], v[142:145]
	v_mfma_f32_16x16x32_bf16 v[138:141], v[100:103], v[194:197], v[138:141]
	v_mfma_f32_16x16x32_bf16 v[124:127], v[76:79], v[216:219], v[124:127]
	v_mfma_f32_16x16x32_bf16 v[120:123], v[100:103], v[216:219], v[120:123]
	v_mfma_f32_16x16x32_bf16 v[108:111], v[76:79], v[224:227], v[108:111]
	v_mfma_f32_16x16x32_bf16 v[104:107], v[100:103], v[224:227], v[104:107]
	v_mfma_f32_16x16x32_bf16 v[84:87], v[76:79], v[232:235], v[84:87]
	v_mfma_f32_16x16x32_bf16 v[80:83], v[100:103], v[232:235], v[80:83]
	v_mfma_f32_16x16x32_bf16 v[132:135], v[146:149], v[172:175], v[132:135]
	v_mfma_f32_16x16x32_bf16 v[128:131], v[154:157], v[172:175], v[128:131]
	v_mfma_f32_16x16x32_bf16 v[116:119], v[146:149], v[198:201], v[116:119]
	v_mfma_f32_16x16x32_bf16 v[112:115], v[154:157], v[198:201], v[112:115]
	v_mfma_f32_16x16x32_bf16 v[96:99], v[146:149], v[220:223], v[96:99]
	v_mfma_f32_16x16x32_bf16 v[92:95], v[154:157], v[220:223], v[92:95]
	v_mfma_f32_16x16x32_bf16 v[72:75], v[146:149], v[228:231], v[72:75]
	v_mfma_f32_16x16x32_bf16 v[68:71], v[154:157], v[228:231], v[68:71]
	v_mfma_f32_16x16x32_bf16 v[132:135], v[150:153], v[194:197], v[132:135]
	v_mfma_f32_16x16x32_bf16 v[128:131], v[158:161], v[194:197], v[128:131]
	v_mfma_f32_16x16x32_bf16 v[116:119], v[150:153], v[216:219], v[116:119]
	v_mfma_f32_16x16x32_bf16 v[112:115], v[158:161], v[216:219], v[112:115]
	v_mfma_f32_16x16x32_bf16 v[96:99], v[150:153], v[224:227], v[96:99]
	v_mfma_f32_16x16x32_bf16 v[92:95], v[158:161], v[224:227], v[92:95]
	v_mfma_f32_16x16x32_bf16 v[72:75], v[150:153], v[232:235], v[72:75]
	v_mfma_f32_16x16x32_bf16 v[68:71], v[158:161], v[232:235], v[68:71]
	s_setprio 0
	s_barrier
; #define PG8_STAGE(bufoff, gbase, voff) do { _Pragma("unroll") for (int _i = 0; _i < 2; ++_i) \
;         __builtin_amdgcn_global_load_lds((const unsigned*)((const char*)(gbase) + (voff)[_i]), (LAS unsigned*)(lds + (bufoff) + ldsw + _i * 8192), 16, 0, 0); } while (0)
; #define PG8_LDA(dst, b, h) do { _Pragma("unroll") for (int m = 0; m < 4; ++m) _Pragma("unroll") for (int k = 0; k < 2; ++k) dst[m][k] = *(const LAS bf16x8*)(lds + PG8_SA(b, h) + aoff + m * 2048 + k * 1024); } while (0)
; #define PG8_MMA(ai, bj, At, Bt) do { __builtin_amdgcn_s_setprio(1); _Pragma("unroll") for (int m = 0; m < 4; ++m) _Pragma("unroll") for (int n = 0; n < 2; ++n) _Pragma("unroll") for (int k = 0; k < 2; ++k) \
;         acc[ai][bj][m][n] = __builtin_amdgcn_mfma_f32_16x16x32_bf16(Bt[n][k], At[m][k], acc[ai][bj][m][n], 0, 0, 0); __builtin_amdgcn_s_setprio(0); } while (0)
; #define PG8_WAIT_V(n) asm volatile("s_waitcnt vmcnt(" #n ")" ::: "memory")
; #define PG8_WAIT_L(n) asm volatile("s_waitcnt lgkmcnt(" #n ")" ::: "memory")
; #define PG8_BAR __builtin_amdgcn_s_barrier()
; #define PG8_SCHED __builtin_amdgcn_sched_barrier(0)
; template <class Epi>
; __device__ __forceinline__ void gemm_phase(LAS unsigned char* lds, const Gemm g, const StaticOrder& S, const Epi& E, const int tid) {
;     ...
;             PG8_LDA(At, 1, 1); PG8_STAGE(PG8_SB(1, 0), b3, voffB); PG8_STAGE(PG8_SB(1, 1), b3 + hstepB, voffB); PG8_STAGE(PG8_SA(1, 0), a3, voffA);
;             PG8_WAIT_V(8); PG8_WAIT_L(0); PG8_BAR; PG8_MMA(1, 0, At, B0); PG8_MMA(1, 1, At, B1); PG8_BAR; PG8_SCHED;
;         }
;         if (wr == 0) PG8_BAR;
	s_add_i32 s30, s54, s39
	v_lshl_add_u64 v[176:177], v[176:177], 0, s[56:57]
	s_mov_b32 m0, s30
	ds_read_b128 v[172:175], v193 offset:49152
	ds_read_b128 v[194:197], v193 offset:50176
	ds_read_b128 v[198:201], v193 offset:51200
	ds_read_b128 v[216:219], v193 offset:52224
	ds_read_b128 v[220:223], v193 offset:53248
	ds_read_b128 v[224:227], v193 offset:54272
	ds_read_b128 v[228:231], v193 offset:55296
	ds_read_b128 v[232:235], v193 offset:56320
	global_load_lds_dwordx4 v[176:177], off
	s_add_i32 m0, s30, 0x2000
	s_add_u32 s28, s28, 0x80080
	v_lshl_add_u64 v[176:177], v[190:191], 0, s[56:57]
	s_addc_u32 s29, s29, 0
	s_add_i32 s30, s55, s39
	global_load_lds_dwordx4 v[176:177], off
	v_lshl_add_u64 v[176:177], s[28:29], 0, v[136:137]
	s_mov_b32 m0, s30
	s_nop 0
	global_load_lds_dwordx4 v[176:177], off
	v_lshl_add_u64 v[176:177], s[28:29], 0, v[162:163]
	s_add_i32 m0, s30, 0x2000
	s_nop 0
	global_load_lds_dwordx4 v[176:177], off
	v_lshl_add_u64 v[176:177], v[202:203], 0, s[56:57]
	s_mov_b32 m0, s44
	s_nop 0
	global_load_lds_dwordx4 v[176:177], off
	v_lshl_add_u64 v[176:177], v[236:237], 0, s[56:57]
	s_mov_b32 m0, s45
	s_nop 0
	global_load_lds_dwordx4 v[176:177], off
	s_waitcnt vmcnt(8)
	s_waitcnt lgkmcnt(0)
	s_barrier
	s_setprio 1
	s_waitcnt lgkmcnt(0)
	v_mfma_f32_16x16x32_bf16 v[60:63], v[64:67], v[172:175], v[60:63]
	v_mfma_f32_16x16x32_bf16 v[56:59], v[88:91], v[172:175], v[56:59]
	v_mfma_f32_16x16x32_bf16 v[44:47], v[64:67], v[198:201], v[44:47]
	v_mfma_f32_16x16x32_bf16 v[40:43], v[88:91], v[198:201], v[40:43]
	v_mfma_f32_16x16x32_bf16 v[28:31], v[64:67], v[220:223], v[28:31]
	v_mfma_f32_16x16x32_bf16 v[24:27], v[88:91], v[220:223], v[24:27]
	v_mfma_f32_16x16x32_bf16 v[12:15], v[64:67], v[228:231], v[12:15]
	v_mfma_f32_16x16x32_bf16 v[8:11], v[88:91], v[228:231], v[8:11]
	v_mfma_f32_16x16x32_bf16 v[60:63], v[76:79], v[194:197], v[60:63]
	v_mfma_f32_16x16x32_bf16 v[56:59], v[100:103], v[194:197], v[56:59]
	v_mfma_f32_16x16x32_bf16 v[44:47], v[76:79], v[216:219], v[44:47]
	v_mfma_f32_16x16x32_bf16 v[40:43], v[100:103], v[216:219], v[40:43]
	v_mfma_f32_16x16x32_bf16 v[28:31], v[76:79], v[224:227], v[28:31]
	v_mfma_f32_16x16x32_bf16 v[24:27], v[100:103], v[224:227], v[24:27]
	v_mfma_f32_16x16x32_bf16 v[12:15], v[76:79], v[232:235], v[12:15]
	v_mfma_f32_16x16x32_bf16 v[8:11], v[100:103], v[232:235], v[8:11]
	v_mfma_f32_16x16x32_bf16 v[52:55], v[146:149], v[172:175], v[52:55]
	v_mfma_f32_16x16x32_bf16 v[48:51], v[154:157], v[172:175], v[48:51]
	v_mfma_f32_16x16x32_bf16 v[36:39], v[146:149], v[198:201], v[36:39]
	v_mfma_f32_16x16x32_bf16 v[32:35], v[154:157], v[198:201], v[32:35]
	v_mfma_f32_16x16x32_bf16 v[20:23], v[146:149], v[220:223], v[20:23]
	v_mfma_f32_16x16x32_bf16 v[16:19], v[154:157], v[220:223], v[16:19]
	v_mfma_f32_16x16x32_bf16 v[4:7], v[146:149], v[228:231], v[4:7]
	v_mfma_f32_16x16x32_bf16 v[0:3], v[154:157], v[228:231], v[0:3]
	v_mfma_f32_16x16x32_bf16 v[52:55], v[150:153], v[194:197], v[52:55]
	v_mfma_f32_16x16x32_bf16 v[48:51], v[158:161], v[194:197], v[48:51]
	v_mfma_f32_16x16x32_bf16 v[36:39], v[150:153], v[216:219], v[36:39]
	v_mfma_f32_16x16x32_bf16 v[32:35], v[158:161], v[216:219], v[32:35]
	v_mfma_f32_16x16x32_bf16 v[20:23], v[150:153], v[224:227], v[20:23]
	v_mfma_f32_16x16x32_bf16 v[16:19], v[158:161], v[224:227], v[16:19]
	v_mfma_f32_16x16x32_bf16 v[4:7], v[150:153], v[232:235], v[4:7]
	v_mfma_f32_16x16x32_bf16 v[0:3], v[158:161], v[232:235], v[0:3]
	s_setprio 0
	s_barrier
	s_add_i32 s53, s53, 2
	s_add_u32 s6, s6, 0x100
	s_addc_u32 s7, s7, 0
	s_add_u32 s51, s51, 0x100
	s_addc_u32 s52, s52, 0
	s_cmp_gt_u32 s53, 13
	s_cbranch_scc0 .LBB0_35
	s_and_b64 vcc, exec, s[12:13]
	s_cbranch_vccz .LBB0_38
	s_barrier

; #define PG8_STAGE(bufoff, gbase, voff) do { _Pragma("unroll") for (int _i = 0; _i < 2; ++_i) \
;         __builtin_amdgcn_global_load_lds((const unsigned*)((const char*)(gbase) + (voff)[_i]), (LAS unsigned*)(lds + (bufoff) + ldsw + _i * 8192), 16, 0, 0); } while (0)
; #define PG8_LDA(dst, b, h) do { _Pragma("unroll") for (int m = 0; m < 4; ++m) _Pragma("unroll") for (int k = 0; k < 2; ++k) dst[m][k] = *(const LAS bf16x8*)(lds + PG8_SA(b, h) + aoff + m * 2048 + k * 1024); } while (0)
; #define PG8_LDB(dst, b, h) do { _Pragma("unroll") for (int n = 0; n < 2; ++n) _Pragma("unroll") for (int k = 0; k < 2; ++k) dst[n][k] = *(const LAS bf16x8*)(lds + PG8_SB(b, h) + boff + n * 2048 + k * 1024); } while (0)
; #define PG8_MMA(ai, bj, At, Bt) do { __builtin_amdgcn_s_setprio(1); _Pragma("unroll") for (int m = 0; m < 4; ++m) _Pragma("unroll") for (int n = 0; n < 2; ++n) _Pragma("unroll") for (int k = 0; k < 2; ++k) \
;         acc[ai][bj][m][n] = __builtin_amdgcn_mfma_f32_16x16x32_bf16(Bt[n][k], At[m][k], acc[ai][bj][m][n], 0, 0, 0); __builtin_amdgcn_s_setprio(0); } while (0)
; #define PG8_WAIT_V(n) asm volatile("s_waitcnt vmcnt(" #n ")" ::: "memory")
; #define PG8_WAIT_L(n) asm volatile("s_waitcnt lgkmcnt(" #n ")" ::: "memory")
; #define PG8_BAR __builtin_amdgcn_s_barrier()
; #define PG8_SCHED __builtin_amdgcn_sched_barrier(0)
; template <class Epi>
; __device__ __forceinline__ void gemm_phase(LAS unsigned char* lds, const Gemm g, const StaticOrder& S, const Epi& E, const int tid) {
;     ...
;             PG8_LDB(B0, 0, 0); PG8_LDB(B1, 0, 1); PG8_SCHED; PG8_LDA(At, 0, 0); PG8_STAGE(PG8_SA(1, 1), a1 + hstepA, voffA);
;             PG8_WAIT_V(8); PG8_WAIT_L(0); PG8_BAR; PG8_MMA(0, 0, At, B0); PG8_MMA(0, 1, At, B1); PG8_BAR; PG8_SCHED;
;             PG8_LDA(At, 0, 1); PG8_STAGE(PG8_SB(0, 0), b2, voffB); PG8_STAGE(PG8_SB(0, 1), b2 + hstepB, voffB); PG8_STAGE(PG8_SA(0, 0), a2, voffA);
;             PG8_WAIT_V(8); PG8_WAIT_L(0); PG8_BAR; PG8_MMA(1, 0, At, B0); PG8_MMA(1, 1, At, B1); PG8_BAR; PG8_SCHED;
.LBB0_489:
	s_add_u32 s46, s36, 0xfff80080
	s_addc_u32 s47, s37, -1
	s_add_i32 s76, 0, 0x10000
	s_cmp_eq_u32 s51, 28
	s_cselect_b32 s49, s3, s47
	s_cselect_b32 s48, s29, s46
	v_add_u32_e32 v154, s76, v157
	s_cselect_b32 s47, s27, s50
	s_cselect_b32 s46, s39, s45
	s_add_i32 s78, 0, 0x14000
	ds_read_b128 v[128:131], v154
	ds_read_b128 v[132:135], v154 offset:1024
	ds_read_b128 v[150:153], v154 offset:2048
	ds_read_b128 v[160:163], v154 offset:3072
	v_add_u32_e32 v154, s78, v157
	ds_read_b128 v[164:167], v154
	ds_read_b128 v[168:171], v154 offset:1024
	ds_read_b128 v[172:175], v154 offset:2048
	ds_read_b128 v[190:193], v154 offset:3072
	v_lshl_add_u64 v[154:155], s[36:37], 0, v[146:147]
	s_add_i32 m0, s55, 0xc000
	ds_read_b128 v[194:197], v159
	ds_read_b128 v[198:201], v159 offset:1024
	ds_read_b128 v[216:219], v159 offset:2048
	ds_read_b128 v[220:223], v159 offset:3072
	ds_read_b128 v[224:227], v159 offset:4096
	ds_read_b128 v[228:231], v159 offset:5120
	ds_read_b128 v[232:235], v159 offset:6144
	ds_read_b128 v[236:239], v159 offset:7168
	global_load_lds_dwordx4 v[154:155], off
	v_lshl_add_u64 v[154:155], s[36:37], 0, v[148:149]
	s_add_i32 m0, s55, 0xe000
	s_nop 0
	global_load_lds_dwordx4 v[154:155], off
	s_waitcnt vmcnt(8)
	s_waitcnt lgkmcnt(0)
	s_barrier
	s_setprio 1
	s_waitcnt lgkmcnt(0)
	v_mfma_f32_16x16x32_bf16 v[56:59], v[128:131], v[194:197], v[56:59]
	v_mfma_f32_16x16x32_bf16 v[60:63], v[150:153], v[194:197], v[60:63]
	v_mfma_f32_16x16x32_bf16 v[48:51], v[128:131], v[216:219], v[48:51]
	v_mfma_f32_16x16x32_bf16 v[52:55], v[150:153], v[216:219], v[52:55]
	v_mfma_f32_16x16x32_bf16 v[40:43], v[128:131], v[224:227], v[40:43]
	v_mfma_f32_16x16x32_bf16 v[44:47], v[150:153], v[224:227], v[44:47]
	v_mfma_f32_16x16x32_bf16 v[32:35], v[128:131], v[232:235], v[32:35]
	v_mfma_f32_16x16x32_bf16 v[36:39], v[150:153], v[232:235], v[36:39]
	v_mfma_f32_16x16x32_bf16 v[56:59], v[132:135], v[198:201], v[56:59]
	v_mfma_f32_16x16x32_bf16 v[60:63], v[160:163], v[198:201], v[60:63]
	v_mfma_f32_16x16x32_bf16 v[48:51], v[132:135], v[220:223], v[48:51]
	v_mfma_f32_16x16x32_bf16 v[52:55], v[160:163], v[220:223], v[52:55]
	v_mfma_f32_16x16x32_bf16 v[40:43], v[132:135], v[228:231], v[40:43]
	v_mfma_f32_16x16x32_bf16 v[44:47], v[160:163], v[228:231], v[44:47]
	v_mfma_f32_16x16x32_bf16 v[32:35], v[132:135], v[236:239], v[32:35]
	v_mfma_f32_16x16x32_bf16 v[36:39], v[160:163], v[236:239], v[36:39]
	v_mfma_f32_16x16x32_bf16 v[120:123], v[164:167], v[194:197], v[120:123]
	v_mfma_f32_16x16x32_bf16 v[124:127], v[172:175], v[194:197], v[124:127]
	v_mfma_f32_16x16x32_bf16 v[112:115], v[164:167], v[216:219], v[112:115]
	v_mfma_f32_16x16x32_bf16 v[116:119], v[172:175], v[216:219], v[116:119]
	v_mfma_f32_16x16x32_bf16 v[104:107], v[164:167], v[224:227], v[104:107]
	v_mfma_f32_16x16x32_bf16 v[108:111], v[172:175], v[224:227], v[108:111]
	v_mfma_f32_16x16x32_bf16 v[96:99], v[164:167], v[232:235], v[96:99]
	v_mfma_f32_16x16x32_bf16 v[100:103], v[172:175], v[232:235], v[100:103]
	v_mfma_f32_16x16x32_bf16 v[120:123], v[168:171], v[198:201], v[120:123]
	v_mfma_f32_16x16x32_bf16 v[124:127], v[190:193], v[198:201], v[124:127]
	v_mfma_f32_16x16x32_bf16 v[112:115], v[168:171], v[220:223], v[112:115]
	v_mfma_f32_16x16x32_bf16 v[116:119], v[190:193], v[220:223], v[116:119]
	v_mfma_f32_16x16x32_bf16 v[104:107], v[168:171], v[228:231], v[104:107]
	v_mfma_f32_16x16x32_bf16 v[108:111], v[190:193], v[228:231], v[108:111]
	v_mfma_f32_16x16x32_bf16 v[96:99], v[168:171], v[236:239], v[96:99]
	v_mfma_f32_16x16x32_bf16 v[100:103], v[190:193], v[236:239], v[100:103]
	s_setprio 0
	s_barrier
	s_add_i32 s76, s76, s54
	v_lshl_add_u64 v[154:155], s[46:47], 0, v[136:137]
	s_mov_b32 m0, s76
	ds_read_b128 v[194:197], v159 offset:16384
	ds_read_b128 v[198:201], v159 offset:17408
	ds_read_b128 v[216:219], v159 offset:18432
	ds_read_b128 v[220:223], v159 offset:19456
	ds_read_b128 v[224:227], v159 offset:20480
	ds_read_b128 v[228:231], v159 offset:21504
	ds_read_b128 v[232:235], v159 offset:22528
	ds_read_b128 v[236:239], v159 offset:23552
	global_load_lds_dwordx4 v[154:155], off
	s_add_i32 m0, s76, 0x2000
	s_add_u32 s76, s46, 0x80000
	v_lshl_add_u64 v[176:177], s[46:47], 0, v[142:143]
	s_addc_u32 s77, s47, 0
	s_add_i32 s78, s78, s54
	global_load_lds_dwordx4 v[176:177], off
	v_lshl_add_u64 v[202:203], s[76:77], 0, v[136:137]
	s_mov_b32 m0, s78
	v_lshl_add_u64 v[240:241], s[48:49], 0, v[140:141]
	global_load_lds_dwordx4 v[202:203], off
	v_lshl_add_u64 v[202:203], s[76:77], 0, v[142:143]
	s_add_i32 m0, s78, 0x2000
	s_nop 0
	global_load_lds_dwordx4 v[202:203], off
	v_lshl_add_u64 v[202:203], s[48:49], 0, v[138:139]
	s_mov_b32 m0, s55
	s_nop 0
	global_load_lds_dwordx4 v[202:203], off
	s_mov_b32 m0, s68
	s_nop 0
	global_load_lds_dwordx4 v[240:241], off
	s_waitcnt vmcnt(8)
	s_waitcnt lgkmcnt(0)
	s_barrier
; #define PG8_STAGE(bufoff, gbase, voff) do { _Pragma("unroll") for (int _i = 0; _i < 2; ++_i) \
;         __builtin_amdgcn_global_load_lds((const unsigned*)((const char*)(gbase) + (voff)[_i]), (LAS unsigned*)(lds + (bufoff) + ldsw + _i * 8192), 16, 0, 0); } while (0)
; #define PG8_LDA(dst, b, h) do { _Pragma("unroll") for (int m = 0; m < 4; ++m) _Pragma("unroll") for (int k = 0; k < 2; ++k) dst[m][k] = *(const LAS bf16x8*)(lds + PG8_SA(b, h) + aoff + m * 2048 + k * 1024); } while (0)
; #define PG8_LDB(dst, b, h) do { _Pragma("unroll") for (int n = 0; n < 2; ++n) _Pragma("unroll") for (int k = 0; k < 2; ++k) dst[n][k] = *(const LAS bf16x8*)(lds + PG8_SB(b, h) + boff + n * 2048 + k * 1024); } while (0)
; #define PG8_MMA(ai, bj, At, Bt) do { __builtin_amdgcn_s_setprio(1); _Pragma("unroll") for (int m = 0; m < 4; ++m) _Pragma("unroll") for (int n = 0; n < 2; ++n) _Pragma("unroll") for (int k = 0; k < 2; ++k) \
;         acc[ai][bj][m][n] = __builtin_amdgcn_mfma_f32_16x16x32_bf16(Bt[n][k], At[m][k], acc[ai][bj][m][n], 0, 0, 0); __builtin_amdgcn_s_setprio(0); } while (0)
; #define PG8_WAIT_V(n) asm volatile("s_waitcnt vmcnt(" #n ")" ::: "memory")
; #define PG8_WAIT_L(n) asm volatile("s_waitcnt lgkmcnt(" #n ")" ::: "memory")
; #define PG8_BAR __builtin_amdgcn_s_barrier()
; #define PG8_SCHED __builtin_amdgcn_sched_barrier(0)
; template <class Epi>
; __device__ __forceinline__ void gemm_phase(LAS unsigned char* lds, const Gemm g, const StaticOrder& S, const Epi& E, const int tid) {
;     ...
;             PG8_WAIT_V(8); PG8_WAIT_L(0); PG8_BAR; PG8_MMA(1, 0, At, B0); PG8_MMA(1, 1, At, B1); PG8_BAR; PG8_SCHED;
;             PG8_LDB(B0, 1, 0); PG8_LDB(B1, 1, 1); PG8_SCHED; PG8_LDA(At, 1, 0); PG8_STAGE(PG8_SA(0, 1), a2 + hstepA, voffA);
;             PG8_WAIT_V(8); PG8_WAIT_L(0); PG8_BAR; PG8_MMA(0, 0, At, B0); PG8_MMA(0, 1, At, B1); PG8_BAR; PG8_SCHED;
	s_setprio 1
	s_waitcnt lgkmcnt(0)
	v_mfma_f32_16x16x32_bf16 v[24:27], v[128:131], v[194:197], v[24:27]
	v_mfma_f32_16x16x32_bf16 v[28:31], v[150:153], v[194:197], v[28:31]
	v_mfma_f32_16x16x32_bf16 v[16:19], v[128:131], v[216:219], v[16:19]
	v_mfma_f32_16x16x32_bf16 v[20:23], v[150:153], v[216:219], v[20:23]
	v_mfma_f32_16x16x32_bf16 v[8:11], v[128:131], v[224:227], v[8:11]
	v_mfma_f32_16x16x32_bf16 v[12:15], v[150:153], v[224:227], v[12:15]
	v_mfma_f32_16x16x32_bf16 v[0:3], v[128:131], v[232:235], v[0:3]
	v_mfma_f32_16x16x32_bf16 v[4:7], v[150:153], v[232:235], v[4:7]
	v_mfma_f32_16x16x32_bf16 v[24:27], v[132:135], v[198:201], v[24:27]
	v_mfma_f32_16x16x32_bf16 v[28:31], v[160:163], v[198:201], v[28:31]
	v_mfma_f32_16x16x32_bf16 v[16:19], v[132:135], v[220:223], v[16:19]
	v_mfma_f32_16x16x32_bf16 v[20:23], v[160:163], v[220:223], v[20:23]
	v_mfma_f32_16x16x32_bf16 v[8:11], v[132:135], v[228:231], v[8:11]
	v_mfma_f32_16x16x32_bf16 v[12:15], v[160:163], v[228:231], v[12:15]
	v_mfma_f32_16x16x32_bf16 v[0:3], v[132:135], v[236:239], v[0:3]
	v_mfma_f32_16x16x32_bf16 v[4:7], v[160:163], v[236:239], v[4:7]
	v_mfma_f32_16x16x32_bf16 v[88:91], v[164:167], v[194:197], v[88:91]
	v_mfma_f32_16x16x32_bf16 v[92:95], v[172:175], v[194:197], v[92:95]
	v_mfma_f32_16x16x32_bf16 v[80:83], v[164:167], v[216:219], v[80:83]
	v_mfma_f32_16x16x32_bf16 v[84:87], v[172:175], v[216:219], v[84:87]
	v_mfma_f32_16x16x32_bf16 v[72:75], v[164:167], v[224:227], v[72:75]
	v_mfma_f32_16x16x32_bf16 v[76:79], v[172:175], v[224:227], v[76:79]
	v_mfma_f32_16x16x32_bf16 v[64:67], v[164:167], v[232:235], v[64:67]
	v_mfma_f32_16x16x32_bf16 v[68:71], v[172:175], v[232:235], v[68:71]
	v_mfma_f32_16x16x32_bf16 v[88:91], v[168:171], v[198:201], v[88:91]
	v_mfma_f32_16x16x32_bf16 v[92:95], v[190:193], v[198:201], v[92:95]
	v_mfma_f32_16x16x32_bf16 v[80:83], v[168:171], v[220:223], v[80:83]
	v_mfma_f32_16x16x32_bf16 v[84:87], v[190:193], v[220:223], v[84:87]
	v_mfma_f32_16x16x32_bf16 v[72:75], v[168:171], v[228:231], v[72:75]
	v_mfma_f32_16x16x32_bf16 v[76:79], v[190:193], v[228:231], v[76:79]
	v_mfma_f32_16x16x32_bf16 v[64:67], v[168:171], v[236:239], v[64:67]
	v_mfma_f32_16x16x32_bf16 v[68:71], v[190:193], v[236:239], v[68:71]
	s_setprio 0
	s_barrier
	s_add_i32 s76, 0, 0x18000
	s_add_i32 s77, 0, 0x1c000
	v_add_u32_e32 v160, s76, v157
	v_add_u32_e32 v187, s77, v157
	ds_read_b128 v[128:131], v160
	ds_read_b128 v[132:135], v160 offset:1024
	ds_read_b128 v[150:153], v160 offset:2048
	ds_read_b128 v[160:163], v160 offset:3072
	ds_read_b128 v[164:167], v187
	ds_read_b128 v[168:171], v187 offset:1024
	ds_read_b128 v[172:175], v187 offset:2048
	ds_read_b128 v[190:193], v187 offset:3072
	s_add_u32 s48, s48, 0x80000
	s_addc_u32 s49, s49, 0
	s_mov_b32 m0, s69
	v_lshl_add_u64 v[242:243], s[48:49], 0, v[138:139]
	ds_read_b128 v[194:197], v159 offset:32768
	ds_read_b128 v[198:201], v159 offset:33792
	ds_read_b128 v[216:219], v159 offset:34816
	ds_read_b128 v[220:223], v159 offset:35840
	ds_read_b128 v[224:227], v159 offset:36864
	ds_read_b128 v[228:231], v159 offset:37888
	ds_read_b128 v[232:235], v159 offset:38912
	ds_read_b128 v[236:239], v159 offset:39936
	global_load_lds_dwordx4 v[242:243], off
	v_lshl_add_u64 v[242:243], s[48:49], 0, v[140:141]
	s_mov_b32 m0, s70
	s_nop 0
	global_load_lds_dwordx4 v[242:243], off
	s_waitcnt vmcnt(8)
	s_waitcnt lgkmcnt(0)
	s_barrier
	s_setprio 1
	s_waitcnt lgkmcnt(0)
	v_mfma_f32_16x16x32_bf16 v[56:59], v[128:131], v[194:197], v[56:59]
	v_mfma_f32_16x16x32_bf16 v[60:63], v[150:153], v[194:197], v[60:63]
	v_mfma_f32_16x16x32_bf16 v[48:51], v[128:131], v[216:219], v[48:51]
	v_mfma_f32_16x16x32_bf16 v[52:55], v[150:153], v[216:219], v[52:55]
	v_mfma_f32_16x16x32_bf16 v[40:43], v[128:131], v[224:227], v[40:43]
	v_mfma_f32_16x16x32_bf16 v[44:47], v[150:153], v[224:227], v[44:47]
	v_mfma_f32_16x16x32_bf16 v[32:35], v[128:131], v[232:235], v[32:35]
	v_mfma_f32_16x16x32_bf16 v[36:39], v[150:153], v[232:235], v[36:39]
	v_mfma_f32_16x16x32_bf16 v[56:59], v[132:135], v[198:201], v[56:59]
	v_mfma_f32_16x16x32_bf16 v[60:63], v[160:163], v[198:201], v[60:63]
	v_mfma_f32_16x16x32_bf16 v[48:51], v[132:135], v[220:223], v[48:51]
	v_mfma_f32_16x16x32_bf16 v[52:55], v[160:163], v[220:223], v[52:55]
	v_mfma_f32_16x16x32_bf16 v[40:43], v[132:135], v[228:231], v[40:43]
	v_mfma_f32_16x16x32_bf16 v[44:47], v[160:163], v[228:231], v[44:47]
	v_mfma_f32_16x16x32_bf16 v[32:35], v[132:135], v[236:239], v[32:35]
	v_mfma_f32_16x16x32_bf16 v[36:39], v[160:163], v[236:239], v[36:39]
	v_mfma_f32_16x16x32_bf16 v[120:123], v[164:167], v[194:197], v[120:123]
	v_mfma_f32_16x16x32_bf16 v[124:127], v[172:175], v[194:197], v[124:127]
	v_mfma_f32_16x16x32_bf16 v[112:115], v[164:167], v[216:219], v[112:115]
	v_mfma_f32_16x16x32_bf16 v[116:119], v[172:175], v[216:219], v[116:119]
	v_mfma_f32_16x16x32_bf16 v[104:107], v[164:167], v[224:227], v[104:107]
	v_mfma_f32_16x16x32_bf16 v[108:111], v[172:175], v[224:227], v[108:111]
	v_mfma_f32_16x16x32_bf16 v[96:99], v[164:167], v[232:235], v[96:99]
	v_mfma_f32_16x16x32_bf16 v[100:103], v[172:175], v[232:235], v[100:103]
	v_mfma_f32_16x16x32_bf16 v[120:123], v[168:171], v[198:201], v[120:123]
	v_mfma_f32_16x16x32_bf16 v[124:127], v[190:193], v[198:201], v[124:127]
	v_mfma_f32_16x16x32_bf16 v[112:115], v[168:171], v[220:223], v[112:115]
	v_mfma_f32_16x16x32_bf16 v[116:119], v[190:193], v[220:223], v[116:119]
	v_mfma_f32_16x16x32_bf16 v[104:107], v[168:171], v[228:231], v[104:107]
	v_mfma_f32_16x16x32_bf16 v[108:111], v[190:193], v[228:231], v[108:111]
	v_mfma_f32_16x16x32_bf16 v[96:99], v[168:171], v[236:239], v[96:99]
	v_mfma_f32_16x16x32_bf16 v[100:103], v[190:193], v[236:239], v[100:103]
	s_setprio 0
	s_barrier
; #define PG8_STAGE(bufoff, gbase, voff) do { _Pragma("unroll") for (int _i = 0; _i < 2; ++_i) \
;         __builtin_amdgcn_global_load_lds((const unsigned*)((const char*)(gbase) + (voff)[_i]), (LAS unsigned*)(lds + (bufoff) + ldsw + _i * 8192), 16, 0, 0); } while (0)
; #define PG8_LDA(dst, b, h) do { _Pragma("unroll") for (int m = 0; m < 4; ++m) _Pragma("unroll") for (int k = 0; k < 2; ++k) dst[m][k] = *(const LAS bf16x8*)(lds + PG8_SA(b, h) + aoff + m * 2048 + k * 1024); } while (0)
; #define PG8_MMA(ai, bj, At, Bt) do { __builtin_amdgcn_s_setprio(1); _Pragma("unroll") for (int m = 0; m < 4; ++m) _Pragma("unroll") for (int n = 0; n < 2; ++n) _Pragma("unroll") for (int k = 0; k < 2; ++k) \
;         acc[ai][bj][m][n] = __builtin_amdgcn_mfma_f32_16x16x32_bf16(Bt[n][k], At[m][k], acc[ai][bj][m][n], 0, 0, 0); __builtin_amdgcn_s_setprio(0); } while (0)
; #define PG8_WAIT_V(n) asm volatile("s_waitcnt vmcnt(" #n ")" ::: "memory")
; #define PG8_WAIT_L(n) asm volatile("s_waitcnt lgkmcnt(" #n ")" ::: "memory")
; #define PG8_BAR __builtin_amdgcn_s_barrier()
; #define PG8_SCHED __builtin_amdgcn_sched_barrier(0)
; template <class Epi>
; __device__ __forceinline__ void gemm_phase(LAS unsigned char* lds, const Gemm g, const StaticOrder& S, const Epi& E, const int tid) {
;     ...
;             PG8_LDA(At, 1, 1); PG8_STAGE(PG8_SB(1, 0), b3, voffB); PG8_STAGE(PG8_SB(1, 1), b3 + hstepB, voffB); PG8_STAGE(PG8_SA(1, 0), a3, voffA);
;             PG8_WAIT_V(8); PG8_WAIT_L(0); PG8_BAR; PG8_MMA(1, 0, At, B0); PG8_MMA(1, 1, At, B1); PG8_BAR; PG8_SCHED;
;         }
;         if (wr == 0) PG8_BAR;
	s_add_i32 s48, s76, s54
	v_lshl_add_u64 v[154:155], v[154:155], 0, s[56:57]
	s_mov_b32 m0, s48
	ds_read_b128 v[194:197], v159 offset:49152
	ds_read_b128 v[198:201], v159 offset:50176
	ds_read_b128 v[216:219], v159 offset:51200
	ds_read_b128 v[220:223], v159 offset:52224
	ds_read_b128 v[224:227], v159 offset:53248
	ds_read_b128 v[228:231], v159 offset:54272
	ds_read_b128 v[232:235], v159 offset:55296
	ds_read_b128 v[236:239], v159 offset:56320
	global_load_lds_dwordx4 v[154:155], off
	s_add_i32 m0, s48, 0x2000
	s_add_u32 s46, s46, 0x80080
	v_lshl_add_u64 v[154:155], v[176:177], 0, s[56:57]
	s_addc_u32 s47, s47, 0
	s_add_i32 s48, s77, s54
	global_load_lds_dwordx4 v[154:155], off
	v_lshl_add_u64 v[154:155], s[46:47], 0, v[136:137]
	s_mov_b32 m0, s48
	s_nop 0
	global_load_lds_dwordx4 v[154:155], off
	v_lshl_add_u64 v[154:155], s[46:47], 0, v[142:143]
	s_add_i32 m0, s48, 0x2000
	s_nop 0
	global_load_lds_dwordx4 v[154:155], off
	v_lshl_add_u64 v[154:155], v[202:203], 0, s[56:57]
	s_mov_b32 m0, s73
	s_nop 0
	global_load_lds_dwordx4 v[154:155], off
	v_lshl_add_u64 v[154:155], v[240:241], 0, s[56:57]
	s_mov_b32 m0, s74
	s_nop 0
	global_load_lds_dwordx4 v[154:155], off
	s_waitcnt vmcnt(8)
	s_waitcnt lgkmcnt(0)
	s_barrier
	s_setprio 1
	s_waitcnt lgkmcnt(0)
	v_mfma_f32_16x16x32_bf16 v[24:27], v[128:131], v[194:197], v[24:27]
	v_mfma_f32_16x16x32_bf16 v[28:31], v[150:153], v[194:197], v[28:31]
	v_mfma_f32_16x16x32_bf16 v[16:19], v[128:131], v[216:219], v[16:19]
	v_mfma_f32_16x16x32_bf16 v[20:23], v[150:153], v[216:219], v[20:23]
	v_mfma_f32_16x16x32_bf16 v[8:11], v[128:131], v[224:227], v[8:11]
	v_mfma_f32_16x16x32_bf16 v[12:15], v[150:153], v[224:227], v[12:15]
	v_mfma_f32_16x16x32_bf16 v[0:3], v[128:131], v[232:235], v[0:3]
	v_mfma_f32_16x16x32_bf16 v[4:7], v[150:153], v[232:235], v[4:7]
	v_mfma_f32_16x16x32_bf16 v[24:27], v[132:135], v[198:201], v[24:27]
	v_mfma_f32_16x16x32_bf16 v[28:31], v[160:163], v[198:201], v[28:31]
	v_mfma_f32_16x16x32_bf16 v[16:19], v[132:135], v[220:223], v[16:19]
	v_mfma_f32_16x16x32_bf16 v[20:23], v[160:163], v[220:223], v[20:23]
	v_mfma_f32_16x16x32_bf16 v[8:11], v[132:135], v[228:231], v[8:11]
	v_mfma_f32_16x16x32_bf16 v[12:15], v[160:163], v[228:231], v[12:15]
	v_mfma_f32_16x16x32_bf16 v[0:3], v[132:135], v[236:239], v[0:3]
	v_mfma_f32_16x16x32_bf16 v[4:7], v[160:163], v[236:239], v[4:7]
	v_mfma_f32_16x16x32_bf16 v[88:91], v[164:167], v[194:197], v[88:91]
	v_mfma_f32_16x16x32_bf16 v[92:95], v[172:175], v[194:197], v[92:95]
	v_mfma_f32_16x16x32_bf16 v[80:83], v[164:167], v[216:219], v[80:83]
	v_mfma_f32_16x16x32_bf16 v[84:87], v[172:175], v[216:219], v[84:87]
	v_mfma_f32_16x16x32_bf16 v[72:75], v[164:167], v[224:227], v[72:75]
	v_mfma_f32_16x16x32_bf16 v[76:79], v[172:175], v[224:227], v[76:79]
	v_mfma_f32_16x16x32_bf16 v[64:67], v[164:167], v[232:235], v[64:67]
	v_mfma_f32_16x16x32_bf16 v[68:71], v[172:175], v[232:235], v[68:71]
	v_mfma_f32_16x16x32_bf16 v[88:91], v[168:171], v[198:201], v[88:91]
	v_mfma_f32_16x16x32_bf16 v[92:95], v[190:193], v[198:201], v[92:95]
	v_mfma_f32_16x16x32_bf16 v[80:83], v[168:171], v[220:223], v[80:83]
	v_mfma_f32_16x16x32_bf16 v[84:87], v[190:193], v[220:223], v[84:87]
	v_mfma_f32_16x16x32_bf16 v[72:75], v[168:171], v[228:231], v[72:75]
	v_mfma_f32_16x16x32_bf16 v[76:79], v[190:193], v[228:231], v[76:79]
	v_mfma_f32_16x16x32_bf16 v[64:67], v[168:171], v[236:239], v[64:67]
	v_mfma_f32_16x16x32_bf16 v[68:71], v[190:193], v[236:239], v[68:71]
	s_setprio 0
	s_barrier
	s_add_i32 s51, s51, 2
	s_add_u32 s36, s36, 0x100
	s_addc_u32 s37, s37, 0
	s_add_u32 s45, s45, 0x100
	s_addc_u32 s50, s50, 0
	s_cmp_gt_u32 s51, 29
	s_cbranch_scc0 .LBB0_489
	s_and_b64 vcc, exec, s[20:21]
	s_cbranch_vccz .LBB0_492
	s_barrier

; #define PG8_STAGE(bufoff, gbase, voff) do { _Pragma("unroll") for (int _i = 0; _i < 2; ++_i) \
;         __builtin_amdgcn_global_load_lds((const unsigned*)((const char*)(gbase) + (voff)[_i]), (LAS unsigned*)(lds + (bufoff) + ldsw + _i * 8192), 16, 0, 0); } while (0)
; #define PG8_LDA(dst, b, h) do { _Pragma("unroll") for (int m = 0; m < 4; ++m) _Pragma("unroll") for (int k = 0; k < 2; ++k) dst[m][k] = *(const LAS bf16x8*)(lds + PG8_SA(b, h) + aoff + m * 2048 + k * 1024); } while (0)
; #define PG8_LDB(dst, b, h) do { _Pragma("unroll") for (int n = 0; n < 2; ++n) _Pragma("unroll") for (int k = 0; k < 2; ++k) dst[n][k] = *(const LAS bf16x8*)(lds + PG8_SB(b, h) + boff + n * 2048 + k * 1024); } while (0)
; #define PG8_MMA(ai, bj, At, Bt) do { __builtin_amdgcn_s_setprio(1); _Pragma("unroll") for (int m = 0; m < 4; ++m) _Pragma("unroll") for (int n = 0; n < 2; ++n) _Pragma("unroll") for (int k = 0; k < 2; ++k) \
;         acc[ai][bj][m][n] = __builtin_amdgcn_mfma_f32_16x16x32_bf16(Bt[n][k], At[m][k], acc[ai][bj][m][n], 0, 0, 0); __builtin_amdgcn_s_setprio(0); } while (0)
; #define PG8_WAIT_V(n) asm volatile("s_waitcnt vmcnt(" #n ")" ::: "memory")
; #define PG8_WAIT_L(n) asm volatile("s_waitcnt lgkmcnt(" #n ")" ::: "memory")
; #define PG8_BAR __builtin_amdgcn_s_barrier()
; #define PG8_SCHED __builtin_amdgcn_sched_barrier(0)
; template <class Epi>
; __device__ __forceinline__ void gemm_phase(LAS unsigned char* lds, const Gemm g, const StaticOrder& S, const Epi& E, const int tid) {
;     ...
;         for (int t = 0; t < nt; t += 2) {
;             const bool last = (t == nt - 2);
;             const char* a1 = cA + (size_t)(t + 1) * kstep;
;             const char* a2 = last ? nA : cA + (size_t)(t + 2) * kstep; const char* b2 = last ? nB : cB + (size_t)(t + 2) * kstep;
;             const char* a3 = a2 + kstep; const char* b3 = b2 + kstep;
;             PG8_LDB(B0, 0, 0); PG8_LDB(B1, 0, 1); PG8_SCHED; PG8_LDA(At, 0, 0); PG8_STAGE(PG8_SA(1, 1), a1 + hstepA, voffA);
;             PG8_WAIT_V(8); PG8_WAIT_L(0); PG8_BAR; PG8_MMA(0, 0, At, B0); PG8_MMA(0, 1, At, B1); PG8_BAR; PG8_SCHED;
;             PG8_LDA(At, 0, 1); PG8_STAGE(PG8_SB(0, 0), b2, voffB); PG8_STAGE(PG8_SB(0, 1), b2 + hstepB, voffB); PG8_STAGE(PG8_SA(0, 0), a2, voffA);
;             PG8_WAIT_V(8); PG8_WAIT_L(0); PG8_BAR; PG8_MMA(1, 0, At, B0); PG8_MMA(1, 1, At, B1); PG8_BAR; PG8_SCHED;
.LBB0_727:
	s_add_u32 s20, s6, 0xfff80080
	s_addc_u32 s21, s7, -1
	s_add_i32 s50, 0, 0x10000
	s_cmp_eq_u32 s49, 28
	s_cselect_b32 s25, s15, s21
	s_cselect_b32 s24, s45, s20
	s_cselect_b32 s21, s13, s48
	s_cselect_b32 s20, s46, s47
	s_add_i32 s52, 0, 0x14000
	v_add_u32_e32 v100, s50, v189
	v_add_u32_e32 v136, s52, v189
	ds_read_b128 v[88:91], v100
	ds_read_b128 v[92:95], v100 offset:1024
	ds_read_b128 v[96:99], v100 offset:2048
	ds_read_b128 v[100:103], v100 offset:3072
	ds_read_b128 v[146:149], v136
	ds_read_b128 v[150:153], v136 offset:1024
	ds_read_b128 v[154:157], v136 offset:2048
	ds_read_b128 v[158:161], v136 offset:3072
	v_lshl_add_u64 v[202:203], s[6:7], 0, v[194:195]
	s_add_i32 m0, s31, 0xc000
	ds_read_b128 v[162:165], v216
	ds_read_b128 v[166:169], v216 offset:1024
	ds_read_b128 v[170:173], v216 offset:2048
	ds_read_b128 v[174:177], v216 offset:3072
	ds_read_b128 v[198:201], v216 offset:4096
	ds_read_b128 v[218:221], v216 offset:5120
	ds_read_b128 v[222:225], v216 offset:6144
	ds_read_b128 v[226:229], v216 offset:7168
	global_load_lds_dwordx4 v[202:203], off
	v_lshl_add_u64 v[202:203], s[6:7], 0, v[196:197]
	s_add_i32 m0, s31, 0xe000
	s_nop 0
	global_load_lds_dwordx4 v[202:203], off
	s_waitcnt vmcnt(8)
	s_waitcnt lgkmcnt(0)
	s_barrier
	s_setprio 1
	s_waitcnt lgkmcnt(0)
	v_mfma_f32_16x16x32_bf16 v[142:145], v[88:91], v[162:165], v[142:145]
	v_mfma_f32_16x16x32_bf16 v[138:141], v[96:99], v[162:165], v[138:141]
	v_mfma_f32_16x16x32_bf16 v[124:127], v[88:91], v[170:173], v[124:127]
	v_mfma_f32_16x16x32_bf16 v[120:123], v[96:99], v[170:173], v[120:123]
	v_mfma_f32_16x16x32_bf16 v[108:111], v[88:91], v[198:201], v[108:111]
	v_mfma_f32_16x16x32_bf16 v[104:107], v[96:99], v[198:201], v[104:107]
	v_mfma_f32_16x16x32_bf16 v[76:79], v[88:91], v[222:225], v[76:79]
	v_mfma_f32_16x16x32_bf16 v[72:75], v[96:99], v[222:225], v[72:75]
	v_mfma_f32_16x16x32_bf16 v[142:145], v[92:95], v[166:169], v[142:145]
	v_mfma_f32_16x16x32_bf16 v[138:141], v[100:103], v[166:169], v[138:141]
	v_mfma_f32_16x16x32_bf16 v[124:127], v[92:95], v[174:177], v[124:127]
	v_mfma_f32_16x16x32_bf16 v[120:123], v[100:103], v[174:177], v[120:123]
	v_mfma_f32_16x16x32_bf16 v[108:111], v[92:95], v[218:221], v[108:111]
	v_mfma_f32_16x16x32_bf16 v[104:107], v[100:103], v[218:221], v[104:107]
	v_mfma_f32_16x16x32_bf16 v[76:79], v[92:95], v[226:229], v[76:79]
	v_mfma_f32_16x16x32_bf16 v[72:75], v[100:103], v[226:229], v[72:75]
	v_mfma_f32_16x16x32_bf16 v[132:135], v[146:149], v[162:165], v[132:135]
	v_mfma_f32_16x16x32_bf16 v[128:131], v[154:157], v[162:165], v[128:131]
	v_mfma_f32_16x16x32_bf16 v[116:119], v[146:149], v[170:173], v[116:119]
	v_mfma_f32_16x16x32_bf16 v[112:115], v[154:157], v[170:173], v[112:115]
	v_mfma_f32_16x16x32_bf16 v[84:87], v[146:149], v[198:201], v[84:87]
	v_mfma_f32_16x16x32_bf16 v[80:83], v[154:157], v[198:201], v[80:83]
	v_mfma_f32_16x16x32_bf16 v[68:71], v[146:149], v[222:225], v[68:71]
	v_mfma_f32_16x16x32_bf16 v[64:67], v[154:157], v[222:225], v[64:67]
	v_mfma_f32_16x16x32_bf16 v[132:135], v[150:153], v[166:169], v[132:135]
	v_mfma_f32_16x16x32_bf16 v[128:131], v[158:161], v[166:169], v[128:131]
	v_mfma_f32_16x16x32_bf16 v[116:119], v[150:153], v[174:177], v[116:119]
	v_mfma_f32_16x16x32_bf16 v[112:115], v[158:161], v[174:177], v[112:115]
	v_mfma_f32_16x16x32_bf16 v[84:87], v[150:153], v[218:221], v[84:87]
	v_mfma_f32_16x16x32_bf16 v[80:83], v[158:161], v[218:221], v[80:83]
	v_mfma_f32_16x16x32_bf16 v[68:71], v[150:153], v[226:229], v[68:71]
	v_mfma_f32_16x16x32_bf16 v[64:67], v[158:161], v[226:229], v[64:67]
	s_setprio 0
	s_barrier
	s_add_i32 s50, s50, s30
	v_lshl_add_u64 v[202:203], s[20:21], 0, v[192:193]
	s_mov_b32 m0, s50
	ds_read_b128 v[162:165], v216 offset:16384
	ds_read_b128 v[166:169], v216 offset:17408
	ds_read_b128 v[170:173], v216 offset:18432
	ds_read_b128 v[174:177], v216 offset:19456
	ds_read_b128 v[198:201], v216 offset:20480
	ds_read_b128 v[218:221], v216 offset:21504
	ds_read_b128 v[222:225], v216 offset:22528
	ds_read_b128 v[226:229], v216 offset:23552
	global_load_lds_dwordx4 v[202:203], off
	s_add_i32 m0, s50, 0x2000
	s_add_u32 s50, s20, 0x80000
	v_lshl_add_u64 v[230:231], s[20:21], 0, v[190:191]
	s_addc_u32 s51, s21, 0
	s_add_i32 s52, s52, s30
	global_load_lds_dwordx4 v[230:231], off
	v_lshl_add_u64 v[232:233], s[50:51], 0, v[192:193]
	s_mov_b32 m0, s52
	v_lshl_add_u64 v[234:235], s[24:25], 0, v[190:191]
	global_load_lds_dwordx4 v[232:233], off
	v_lshl_add_u64 v[232:233], s[50:51], 0, v[190:191]
	s_add_i32 m0, s52, 0x2000
	s_nop 0
	global_load_lds_dwordx4 v[232:233], off
	v_lshl_add_u64 v[232:233], s[24:25], 0, v[192:193]
	s_mov_b32 m0, s31
	s_nop 0
	global_load_lds_dwordx4 v[232:233], off
	s_mov_b32 m0, s34
	s_nop 0
	global_load_lds_dwordx4 v[234:235], off
	s_waitcnt vmcnt(8)
	s_waitcnt lgkmcnt(0)
	s_barrier
; #define PG8_STAGE(bufoff, gbase, voff) do { _Pragma("unroll") for (int _i = 0; _i < 2; ++_i) \
;         __builtin_amdgcn_global_load_lds((const unsigned*)((const char*)(gbase) + (voff)[_i]), (LAS unsigned*)(lds + (bufoff) + ldsw + _i * 8192), 16, 0, 0); } while (0)
; #define PG8_LDA(dst, b, h) do { _Pragma("unroll") for (int m = 0; m < 4; ++m) _Pragma("unroll") for (int k = 0; k < 2; ++k) dst[m][k] = *(const LAS bf16x8*)(lds + PG8_SA(b, h) + aoff + m * 2048 + k * 1024); } while (0)
; #define PG8_LDB(dst, b, h) do { _Pragma("unroll") for (int n = 0; n < 2; ++n) _Pragma("unroll") for (int k = 0; k < 2; ++k) dst[n][k] = *(const LAS bf16x8*)(lds + PG8_SB(b, h) + boff + n * 2048 + k * 1024); } while (0)
; #define PG8_MMA(ai, bj, At, Bt) do { __builtin_amdgcn_s_setprio(1); _Pragma("unroll") for (int m = 0; m < 4; ++m) _Pragma("unroll") for (int n = 0; n < 2; ++n) _Pragma("unroll") for (int k = 0; k < 2; ++k) \
;         acc[ai][bj][m][n] = __builtin_amdgcn_mfma_f32_16x16x32_bf16(Bt[n][k], At[m][k], acc[ai][bj][m][n], 0, 0, 0); __builtin_amdgcn_s_setprio(0); } while (0)
; #define PG8_WAIT_V(n) asm volatile("s_waitcnt vmcnt(" #n ")" ::: "memory")
; #define PG8_WAIT_L(n) asm volatile("s_waitcnt lgkmcnt(" #n ")" ::: "memory")
; #define PG8_BAR __builtin_amdgcn_s_barrier()
; #define PG8_SCHED __builtin_amdgcn_sched_barrier(0)
; template <class Epi>
; __device__ __forceinline__ void gemm_phase(LAS unsigned char* lds, const Gemm g, const StaticOrder& S, const Epi& E, const int tid) {
;     ...
;             PG8_WAIT_V(8); PG8_WAIT_L(0); PG8_BAR; PG8_MMA(1, 0, At, B0); PG8_MMA(1, 1, At, B1); PG8_BAR; PG8_SCHED;
;             PG8_LDB(B0, 1, 0); PG8_LDB(B1, 1, 1); PG8_SCHED; PG8_LDA(At, 1, 0); PG8_STAGE(PG8_SA(0, 1), a2 + hstepA, voffA);
;             PG8_WAIT_V(8); PG8_WAIT_L(0); PG8_BAR; PG8_MMA(0, 0, At, B0); PG8_MMA(0, 1, At, B1); PG8_BAR; PG8_SCHED;
	s_setprio 1
	s_waitcnt lgkmcnt(0)
	v_mfma_f32_16x16x32_bf16 v[60:63], v[88:91], v[162:165], v[60:63]
	v_mfma_f32_16x16x32_bf16 v[56:59], v[96:99], v[162:165], v[56:59]
	v_mfma_f32_16x16x32_bf16 v[44:47], v[88:91], v[170:173], v[44:47]
	v_mfma_f32_16x16x32_bf16 v[40:43], v[96:99], v[170:173], v[40:43]
	v_mfma_f32_16x16x32_bf16 v[28:31], v[88:91], v[198:201], v[28:31]
	v_mfma_f32_16x16x32_bf16 v[24:27], v[96:99], v[198:201], v[24:27]
	v_mfma_f32_16x16x32_bf16 v[12:15], v[88:91], v[222:225], v[12:15]
	v_mfma_f32_16x16x32_bf16 v[8:11], v[96:99], v[222:225], v[8:11]
	v_mfma_f32_16x16x32_bf16 v[60:63], v[92:95], v[166:169], v[60:63]
	v_mfma_f32_16x16x32_bf16 v[56:59], v[100:103], v[166:169], v[56:59]
	v_mfma_f32_16x16x32_bf16 v[44:47], v[92:95], v[174:177], v[44:47]
	v_mfma_f32_16x16x32_bf16 v[40:43], v[100:103], v[174:177], v[40:43]
	v_mfma_f32_16x16x32_bf16 v[28:31], v[92:95], v[218:221], v[28:31]
	v_mfma_f32_16x16x32_bf16 v[24:27], v[100:103], v[218:221], v[24:27]
	v_mfma_f32_16x16x32_bf16 v[12:15], v[92:95], v[226:229], v[12:15]
	v_mfma_f32_16x16x32_bf16 v[8:11], v[100:103], v[226:229], v[8:11]
	v_mfma_f32_16x16x32_bf16 v[52:55], v[146:149], v[162:165], v[52:55]
	v_mfma_f32_16x16x32_bf16 v[48:51], v[154:157], v[162:165], v[48:51]
	v_mfma_f32_16x16x32_bf16 v[36:39], v[146:149], v[170:173], v[36:39]
	v_mfma_f32_16x16x32_bf16 v[32:35], v[154:157], v[170:173], v[32:35]
	v_mfma_f32_16x16x32_bf16 v[20:23], v[146:149], v[198:201], v[20:23]
	v_mfma_f32_16x16x32_bf16 v[16:19], v[154:157], v[198:201], v[16:19]
	v_mfma_f32_16x16x32_bf16 v[4:7], v[146:149], v[222:225], v[4:7]
	v_mfma_f32_16x16x32_bf16 v[0:3], v[154:157], v[222:225], v[0:3]
	v_mfma_f32_16x16x32_bf16 v[52:55], v[150:153], v[166:169], v[52:55]
	v_mfma_f32_16x16x32_bf16 v[48:51], v[158:161], v[166:169], v[48:51]
	v_mfma_f32_16x16x32_bf16 v[36:39], v[150:153], v[174:177], v[36:39]
	v_mfma_f32_16x16x32_bf16 v[32:35], v[158:161], v[174:177], v[32:35]
	v_mfma_f32_16x16x32_bf16 v[20:23], v[150:153], v[218:221], v[20:23]
	v_mfma_f32_16x16x32_bf16 v[16:19], v[158:161], v[218:221], v[16:19]
	v_mfma_f32_16x16x32_bf16 v[4:7], v[150:153], v[226:229], v[4:7]
	v_mfma_f32_16x16x32_bf16 v[0:3], v[158:161], v[226:229], v[0:3]
	s_setprio 0
	s_barrier
	s_add_i32 s50, 0, 0x18000
	s_add_i32 s51, 0, 0x1c000
	v_add_u32_e32 v100, s50, v189
	v_add_u32_e32 v136, s51, v189
	ds_read_b128 v[88:91], v100
	ds_read_b128 v[92:95], v100 offset:1024
	ds_read_b128 v[96:99], v100 offset:2048
	ds_read_b128 v[100:103], v100 offset:3072
	ds_read_b128 v[146:149], v136
	ds_read_b128 v[150:153], v136 offset:1024
	ds_read_b128 v[154:157], v136 offset:2048
	ds_read_b128 v[158:161], v136 offset:3072
	s_add_u32 s24, s24, 0x80000
	s_addc_u32 s25, s25, 0
	s_mov_b32 m0, s35
	v_lshl_add_u64 v[236:237], s[24:25], 0, v[192:193]
	ds_read_b128 v[162:165], v216 offset:32768
	ds_read_b128 v[166:169], v216 offset:33792
	ds_read_b128 v[170:173], v216 offset:34816
	ds_read_b128 v[174:177], v216 offset:35840
	ds_read_b128 v[198:201], v216 offset:36864
	ds_read_b128 v[218:221], v216 offset:37888
	ds_read_b128 v[222:225], v216 offset:38912
	ds_read_b128 v[226:229], v216 offset:39936
	global_load_lds_dwordx4 v[236:237], off
	v_lshl_add_u64 v[236:237], s[24:25], 0, v[190:191]
	s_mov_b32 m0, s36
	s_nop 0
	global_load_lds_dwordx4 v[236:237], off
	s_waitcnt vmcnt(8)
	s_waitcnt lgkmcnt(0)
	s_barrier
	s_setprio 1
	s_waitcnt lgkmcnt(0)
	v_mfma_f32_16x16x32_bf16 v[142:145], v[88:91], v[162:165], v[142:145]
	v_mfma_f32_16x16x32_bf16 v[138:141], v[96:99], v[162:165], v[138:141]
	v_mfma_f32_16x16x32_bf16 v[124:127], v[88:91], v[170:173], v[124:127]
	v_mfma_f32_16x16x32_bf16 v[120:123], v[96:99], v[170:173], v[120:123]
	v_mfma_f32_16x16x32_bf16 v[108:111], v[88:91], v[198:201], v[108:111]
	v_mfma_f32_16x16x32_bf16 v[104:107], v[96:99], v[198:201], v[104:107]
	v_mfma_f32_16x16x32_bf16 v[76:79], v[88:91], v[222:225], v[76:79]
	v_mfma_f32_16x16x32_bf16 v[72:75], v[96:99], v[222:225], v[72:75]
	v_mfma_f32_16x16x32_bf16 v[142:145], v[92:95], v[166:169], v[142:145]
	v_mfma_f32_16x16x32_bf16 v[138:141], v[100:103], v[166:169], v[138:141]
	v_mfma_f32_16x16x32_bf16 v[124:127], v[92:95], v[174:177], v[124:127]
	v_mfma_f32_16x16x32_bf16 v[120:123], v[100:103], v[174:177], v[120:123]
	v_mfma_f32_16x16x32_bf16 v[108:111], v[92:95], v[218:221], v[108:111]
	v_mfma_f32_16x16x32_bf16 v[104:107], v[100:103], v[218:221], v[104:107]
	v_mfma_f32_16x16x32_bf16 v[76:79], v[92:95], v[226:229], v[76:79]
	v_mfma_f32_16x16x32_bf16 v[72:75], v[100:103], v[226:229], v[72:75]
	v_mfma_f32_16x16x32_bf16 v[132:135], v[146:149], v[162:165], v[132:135]
	v_mfma_f32_16x16x32_bf16 v[128:131], v[154:157], v[162:165], v[128:131]
	v_mfma_f32_16x16x32_bf16 v[116:119], v[146:149], v[170:173], v[116:119]
	v_mfma_f32_16x16x32_bf16 v[112:115], v[154:157], v[170:173], v[112:115]
	v_mfma_f32_16x16x32_bf16 v[84:87], v[146:149], v[198:201], v[84:87]
	v_mfma_f32_16x16x32_bf16 v[80:83], v[154:157], v[198:201], v[80:83]
	v_mfma_f32_16x16x32_bf16 v[68:71], v[146:149], v[222:225], v[68:71]
	v_mfma_f32_16x16x32_bf16 v[64:67], v[154:157], v[222:225], v[64:67]
	v_mfma_f32_16x16x32_bf16 v[132:135], v[150:153], v[166:169], v[132:135]
	v_mfma_f32_16x16x32_bf16 v[128:131], v[158:161], v[166:169], v[128:131]
	v_mfma_f32_16x16x32_bf16 v[116:119], v[150:153], v[174:177], v[116:119]
	v_mfma_f32_16x16x32_bf16 v[112:115], v[158:161], v[174:177], v[112:115]
	v_mfma_f32_16x16x32_bf16 v[84:87], v[150:153], v[218:221], v[84:87]
	v_mfma_f32_16x16x32_bf16 v[80:83], v[158:161], v[218:221], v[80:83]
	v_mfma_f32_16x16x32_bf16 v[68:71], v[150:153], v[226:229], v[68:71]
	v_mfma_f32_16x16x32_bf16 v[64:67], v[158:161], v[226:229], v[64:67]
	s_setprio 0
	s_barrier
; #define PG8_STAGE(bufoff, gbase, voff) do { _Pragma("unroll") for (int _i = 0; _i < 2; ++_i) \
;         __builtin_amdgcn_global_load_lds((const unsigned*)((const char*)(gbase) + (voff)[_i]), (LAS unsigned*)(lds + (bufoff) + ldsw + _i * 8192), 16, 0, 0); } while (0)
; #define PG8_LDA(dst, b, h) do { _Pragma("unroll") for (int m = 0; m < 4; ++m) _Pragma("unroll") for (int k = 0; k < 2; ++k) dst[m][k] = *(const LAS bf16x8*)(lds + PG8_SA(b, h) + aoff + m * 2048 + k * 1024); } while (0)
; #define PG8_MMA(ai, bj, At, Bt) do { __builtin_amdgcn_s_setprio(1); _Pragma("unroll") for (int m = 0; m < 4; ++m) _Pragma("unroll") for (int n = 0; n < 2; ++n) _Pragma("unroll") for (int k = 0; k < 2; ++k) \
;         acc[ai][bj][m][n] = __builtin_amdgcn_mfma_f32_16x16x32_bf16(Bt[n][k], At[m][k], acc[ai][bj][m][n], 0, 0, 0); __builtin_amdgcn_s_setprio(0); } while (0)
; #define PG8_WAIT_V(n) asm volatile("s_waitcnt vmcnt(" #n ")" ::: "memory")
; #define PG8_WAIT_L(n) asm volatile("s_waitcnt lgkmcnt(" #n ")" ::: "memory")
; #define PG8_BAR __builtin_amdgcn_s_barrier()
; #define PG8_SCHED __builtin_amdgcn_sched_barrier(0)
; template <class Epi>
; __device__ __forceinline__ void gemm_phase(LAS unsigned char* lds, const Gemm g, const StaticOrder& S, const Epi& E, const int tid) {
;     ...
;             PG8_LDA(At, 1, 1); PG8_STAGE(PG8_SB(1, 0), b3, voffB); PG8_STAGE(PG8_SB(1, 1), b3 + hstepB, voffB); PG8_STAGE(PG8_SA(1, 0), a3, voffA);
;             PG8_WAIT_V(8); PG8_WAIT_L(0); PG8_BAR; PG8_MMA(1, 0, At, B0); PG8_MMA(1, 1, At, B1); PG8_BAR; PG8_SCHED;
;         }
;         if (wr == 0) PG8_BAR;
	s_add_i32 s24, s50, s30
	v_lshl_add_u64 v[202:203], v[202:203], 0, s[56:57]
	s_mov_b32 m0, s24
	ds_read_b128 v[162:165], v216 offset:49152
	ds_read_b128 v[166:169], v216 offset:50176
	ds_read_b128 v[170:173], v216 offset:51200
	ds_read_b128 v[174:177], v216 offset:52224
	ds_read_b128 v[198:201], v216 offset:53248
	ds_read_b128 v[218:221], v216 offset:54272
	ds_read_b128 v[222:225], v216 offset:55296
	ds_read_b128 v[226:229], v216 offset:56320
	global_load_lds_dwordx4 v[202:203], off
	s_add_i32 m0, s24, 0x2000
	s_add_u32 s20, s20, 0x80080
	v_lshl_add_u64 v[202:203], v[230:231], 0, s[56:57]
	s_addc_u32 s21, s21, 0
	s_add_i32 s24, s51, s30
	global_load_lds_dwordx4 v[202:203], off
	v_lshl_add_u64 v[202:203], s[20:21], 0, v[192:193]
	s_mov_b32 m0, s24
	s_nop 0
	global_load_lds_dwordx4 v[202:203], off
	v_lshl_add_u64 v[202:203], s[20:21], 0, v[190:191]
	s_add_i32 m0, s24, 0x2000
	s_nop 0
	global_load_lds_dwordx4 v[202:203], off
	v_lshl_add_u64 v[202:203], v[232:233], 0, s[56:57]
	s_mov_b32 m0, s40
	s_nop 0
	global_load_lds_dwordx4 v[202:203], off
	v_lshl_add_u64 v[202:203], v[234:235], 0, s[56:57]
	s_mov_b32 m0, s41
	s_nop 0
	global_load_lds_dwordx4 v[202:203], off
	s_waitcnt vmcnt(8)
	s_waitcnt lgkmcnt(0)
	s_barrier
	s_setprio 1
	s_waitcnt lgkmcnt(0)
	v_mfma_f32_16x16x32_bf16 v[60:63], v[88:91], v[162:165], v[60:63]
	v_mfma_f32_16x16x32_bf16 v[56:59], v[96:99], v[162:165], v[56:59]
	v_mfma_f32_16x16x32_bf16 v[44:47], v[88:91], v[170:173], v[44:47]
	v_mfma_f32_16x16x32_bf16 v[40:43], v[96:99], v[170:173], v[40:43]
	v_mfma_f32_16x16x32_bf16 v[28:31], v[88:91], v[198:201], v[28:31]
	v_mfma_f32_16x16x32_bf16 v[24:27], v[96:99], v[198:201], v[24:27]
	v_mfma_f32_16x16x32_bf16 v[12:15], v[88:91], v[222:225], v[12:15]
	v_mfma_f32_16x16x32_bf16 v[8:11], v[96:99], v[222:225], v[8:11]
	v_mfma_f32_16x16x32_bf16 v[60:63], v[92:95], v[166:169], v[60:63]
	v_mfma_f32_16x16x32_bf16 v[56:59], v[100:103], v[166:169], v[56:59]
	v_mfma_f32_16x16x32_bf16 v[44:47], v[92:95], v[174:177], v[44:47]
	v_mfma_f32_16x16x32_bf16 v[40:43], v[100:103], v[174:177], v[40:43]
	v_mfma_f32_16x16x32_bf16 v[28:31], v[92:95], v[218:221], v[28:31]
	v_mfma_f32_16x16x32_bf16 v[24:27], v[100:103], v[218:221], v[24:27]
	v_mfma_f32_16x16x32_bf16 v[12:15], v[92:95], v[226:229], v[12:15]
	v_mfma_f32_16x16x32_bf16 v[8:11], v[100:103], v[226:229], v[8:11]
	v_mfma_f32_16x16x32_bf16 v[52:55], v[146:149], v[162:165], v[52:55]
	v_mfma_f32_16x16x32_bf16 v[48:51], v[154:157], v[162:165], v[48:51]
	v_mfma_f32_16x16x32_bf16 v[36:39], v[146:149], v[170:173], v[36:39]
	v_mfma_f32_16x16x32_bf16 v[32:35], v[154:157], v[170:173], v[32:35]
	v_mfma_f32_16x16x32_bf16 v[20:23], v[146:149], v[198:201], v[20:23]
	v_mfma_f32_16x16x32_bf16 v[16:19], v[154:157], v[198:201], v[16:19]
	v_mfma_f32_16x16x32_bf16 v[4:7], v[146:149], v[222:225], v[4:7]
	v_mfma_f32_16x16x32_bf16 v[0:3], v[154:157], v[222:225], v[0:3]
	v_mfma_f32_16x16x32_bf16 v[52:55], v[150:153], v[166:169], v[52:55]
	v_mfma_f32_16x16x32_bf16 v[48:51], v[158:161], v[166:169], v[48:51]
	v_mfma_f32_16x16x32_bf16 v[36:39], v[150:153], v[174:177], v[36:39]
	v_mfma_f32_16x16x32_bf16 v[32:35], v[158:161], v[174:177], v[32:35]
	v_mfma_f32_16x16x32_bf16 v[20:23], v[150:153], v[218:221], v[20:23]
	v_mfma_f32_16x16x32_bf16 v[16:19], v[158:161], v[218:221], v[16:19]
	v_mfma_f32_16x16x32_bf16 v[4:7], v[150:153], v[226:229], v[4:7]
	v_mfma_f32_16x16x32_bf16 v[0:3], v[158:161], v[226:229], v[0:3]
	s_setprio 0
	s_barrier
	s_add_i32 s49, s49, 2
	s_add_u32 s6, s6, 0x100
	s_addc_u32 s7, s7, 0
	s_add_u32 s47, s47, 0x100
	s_addc_u32 s48, s48, 0
	s_cmp_gt_u32 s49, 29
	s_cbranch_scc0 .LBB0_727
	s_and_b64 vcc, exec, s[8:9]
	s_cbranch_vccz .LBB0_730
	s_barrier
